# SWA attention inner loop latency edits: all eight V transpose reads issued before the exp/pack sequence with one wait (was four read-wait-MFMA round trips), relative-position bias reads from one base
# speedup vs baseline: 1.0023x; 1.0023x over previous
.LBB0_1289:
	v_or_b32_e32 v232, s50, v205
	s_movk_i32 s98, 0xc0
	v_mad_u32_u24 v232, v232, s98, v5
	ds_read_b64_tr_b16 v[216:217], v232 offset:9216
	ds_read_b64_tr_b16 v[218:219], v232 offset:10752
	ds_read_b64_tr_b16 v[220:221], v232 offset:12288
	ds_read_b64_tr_b16 v[222:223], v232 offset:13824
	ds_read_b64_tr_b16 v[224:225], v232 offset:9280
	ds_read_b64_tr_b16 v[226:227], v232 offset:10816
	ds_read_b64_tr_b16 v[228:229], v232 offset:12352
	ds_read_b64_tr_b16 v[230:231], v232 offset:13888
	v_sub_f32_e32 v53, v175, v159
	v_exp_f32_e32 v53, v53
	v_sub_f32_e32 v55, v174, v159
	v_exp_f32_e32 v55, v55
	v_sub_f32_e32 v52, v52, v159
	v_exp_f32_e32 v52, v52
	v_sub_f32_e32 v51, v51, v159
	v_exp_f32_e32 v51, v51
	v_sub_f32_e32 v50, v50, v159
	v_add_f32_e32 v54, 0, v53
	v_exp_f32_e32 v50, v50
	v_sub_f32_e32 v17, v17, v159
	v_add_f32_e32 v54, v55, v54
	v_exp_f32_e32 v17, v17
	v_sub_f32_e32 v16, v16, v159
	v_add_f32_e32 v54, v52, v54
	v_exp_f32_e32 v16, v16
	v_sub_f32_e32 v15, v15, v159
	v_add_f32_e32 v54, v51, v54
	v_exp_f32_e32 v15, v15
	v_sub_f32_e32 v14, v14, v159
	v_add_f32_e32 v54, v50, v54
	v_exp_f32_e32 v14, v14
	v_sub_f32_e32 v13, v13, v159
	v_add_f32_e32 v54, v17, v54
	v_exp_f32_e32 v13, v13
	v_sub_f32_e32 v12, v12, v159
	v_add_f32_e32 v54, v16, v54
	v_exp_f32_e32 v56, v12
	v_add_f32_e32 v54, v15, v54
	v_add_f32_e32 v54, v14, v54
	v_add_f32_e32 v54, v13, v54
	v_sub_f32_e32 v11, v11, v159
	v_add_f32_e32 v12, v56, v54
	v_exp_f32_e32 v54, v11
	v_sub_f32_e32 v10, v10, v159
	v_exp_f32_e32 v57, v10
	v_sub_f32_e32 v9, v9, v159
	v_exp_f32_e32 v58, v9
	v_sub_f32_e32 v8, v8, v159
	v_exp_f32_e32 v59, v8
	v_sub_f32_e32 v7, v7, v159
	v_add_f32_e32 v11, v54, v12
	v_exp_f32_e32 v7, v7
	v_add_f32_e32 v10, v57, v11
	v_add_f32_e32 v9, v58, v10
	v_add_f32_e32 v8, v59, v9
	v_add_f32_e32 v60, v7, v8
	v_cvt_pk_bf16_f32 v11, v16, v15
	v_cvt_pk_bf16_f32 v15, v59, v7
	v_cvt_pk_bf16_f32 v8, v53, v55
	v_cvt_pk_bf16_f32 v9, v52, v51
	v_cvt_pk_bf16_f32 v10, v50, v17
	v_cvt_pk_bf16_f32 v12, v14, v13
	v_cvt_pk_bf16_f32 v13, v56, v54
	v_cvt_pk_bf16_f32 v14, v57, v58
	s_xor_b64 s[82:83], s[84:85], -1
	v_add_f32_e32 v3, v3, v60
	s_mov_b32 s50, 32
	s_mov_b64 s[84:85], 0
	s_and_b64 vcc, exec, s[82:83]
	s_waitcnt lgkmcnt(0)
	v_mfma_f32_32x32x16_bf16 v[34:49], v[216:219], v[8:11], v[34:49]
	v_mfma_f32_32x32x16_bf16 v[18:33], v[224:227], v[8:11], v[18:33]
	v_mfma_f32_32x32x16_bf16 v[34:49], v[220:223], v[12:15], v[34:49]
	v_mfma_f32_32x32x16_bf16 v[18:33], v[228:231], v[12:15], v[18:33]
	s_cbranch_vccnz .LBB0_1292
.LBB0_1290:
	v_or_b32_e32 v233, s50, v6
	v_sub_u32_e32 v233, v173, v233
	v_lshl_add_u32 v233, v233, 2, s36
	v_add_u32_e32 v233, 0xffffff94, v233
	ds_read_b32 v234, v233 offset:108
	ds_read_b32 v235, v233 offset:104
	ds_read_b32 v236, v233 offset:100
	ds_read_b32 v237, v233 offset:96
	ds_read_b32 v238, v233 offset:76
	ds_read_b32 v239, v233 offset:72
	ds_read_b32 v240, v233 offset:68
	ds_read_b32 v241, v233 offset:64
	ds_read_b32 v242, v233 offset:44
	ds_read_b32 v243, v233 offset:40
	ds_read_b32 v244, v233 offset:36
	ds_read_b32 v245, v233 offset:32
	ds_read_b32 v246, v233 offset:12
	ds_read_b32 v247, v233 offset:8
	ds_read_b32 v248, v233 offset:4
	ds_read_b32 v249, v233 offset:0
	v_or_b32_e32 v7, s50, v203
	s_movk_i32 s51, 0x90
	v_mad_u32_u24 v7, v7, s51, v4
	ds_read_b128 v[8:11], v7
	ds_read_b128 v[12:15], v7 offset:32
	ds_read_b128 v[174:177], v7 offset:64
	ds_read_b128 v[178:181], v7 offset:96
	v_or_b32_e32 v7, s50, v6
	v_sub_u32_e32 v7, v173, v7
	v_add_u32_e32 v17, -1, v7
	v_add_u32_e32 v183, -2, v7
	v_add_u32_e32 v185, -3, v7
	v_add_u32_e32 v187, -8, v7
	v_add_u32_e32 v189, -9, v7
	v_add_u32_e32 v191, -10, v7
	v_add_u32_e32 v193, -11, v7
	v_add_u32_e32 v195, -16, v7
	v_subrev_u32_e32 v197, 17, v7
	v_subrev_u32_e32 v199, 18, v7
	s_waitcnt lgkmcnt(3)
	v_mfma_f32_32x32x16_bf16 v[50:65], v[8:11], v[130:133], 0
	v_subrev_u32_e32 v211, 19, v7
	v_subrev_u32_e32 v9, 24, v7
	v_subrev_u32_e32 v212, 25, v7
	v_subrev_u32_e32 v213, 26, v7
	v_subrev_u32_e32 v214, 27, v7
	s_waitcnt lgkmcnt(2)
	v_mfma_f32_32x32x16_bf16 v[50:65], v[12:15], v[134:137], v[50:65]
	s_waitcnt lgkmcnt(1)
	v_mfma_f32_32x32x16_bf16 v[50:65], v[174:177], v[138:141], v[50:65]
	s_waitcnt lgkmcnt(0)
	v_mfma_f32_32x32x16_bf16 v[50:65], v[178:181], v[142:145], v[50:65]
	v_cmp_gt_u32_e32 vcc, s65, v7
	s_nop 10
	v_add_f32_e32 v14, v50, v234
	v_cndmask_b32_e32 v175, v172, v14, vcc
	v_add_f32_e32 v7, v51, v235
	v_cmp_gt_u32_e32 vcc, s65, v17
	s_nop 1
	v_cndmask_b32_e32 v174, v172, v7, vcc
	v_add_f32_e32 v7, v52, v236
	v_cmp_gt_u32_e32 vcc, s65, v183
	s_nop 1
	v_cndmask_b32_e32 v52, v172, v7, vcc
	v_add_f32_e32 v7, v53, v237
	v_cmp_gt_u32_e32 vcc, s65, v185
	v_max_f32_e32 v53, v175, v174
	s_nop 0
	v_cndmask_b32_e32 v51, v172, v7, vcc
	v_add_f32_e32 v7, v54, v238
	v_cmp_gt_u32_e32 vcc, s65, v187
	v_max3_f32 v53, v53, v52, v51
	s_nop 0
	v_cndmask_b32_e32 v50, v172, v7, vcc
	v_add_f32_e32 v7, v55, v239
	v_cmp_gt_u32_e32 vcc, s65, v189
	s_nop 1
	v_cndmask_b32_e32 v17, v172, v7, vcc
	v_add_f32_e32 v7, v56, v240
	v_cmp_gt_u32_e32 vcc, s65, v191
	v_max3_f32 v53, v53, v50, v17
	s_nop 0
	v_cndmask_b32_e32 v16, v172, v7, vcc
	v_add_f32_e32 v7, v57, v241
	v_cmp_gt_u32_e32 vcc, s65, v193
	s_nop 1
	v_cndmask_b32_e32 v15, v172, v7, vcc
	v_add_f32_e32 v7, v58, v242
	v_cmp_gt_u32_e32 vcc, s65, v195
	v_max3_f32 v53, v53, v16, v15
	s_nop 0
	v_cndmask_b32_e32 v14, v172, v7, vcc
	v_add_f32_e32 v7, v59, v243
	v_cmp_gt_u32_e32 vcc, s65, v197
	s_nop 1
	v_cndmask_b32_e32 v13, v172, v7, vcc
	v_add_f32_e32 v7, v60, v244
	v_cmp_gt_u32_e32 vcc, s65, v199
	v_max3_f32 v53, v53, v14, v13
	s_nop 0
	v_cndmask_b32_e32 v12, v172, v7, vcc
	v_add_f32_e32 v7, v61, v245
	v_cmp_gt_u32_e32 vcc, s65, v211
	s_nop 1
	v_cndmask_b32_e32 v11, v172, v7, vcc
	v_add_f32_e32 v7, v62, v246
	v_cmp_gt_u32_e32 vcc, s65, v9
	v_max3_f32 v53, v53, v12, v11
	s_nop 0
	v_cndmask_b32_e32 v10, v172, v7, vcc
	v_add_f32_e32 v7, v63, v247
	v_cmp_gt_u32_e32 vcc, s65, v212
	s_nop 1
	v_cndmask_b32_e32 v9, v172, v7, vcc
	v_add_f32_e32 v7, v64, v248
	v_cmp_gt_u32_e32 vcc, s65, v213
	v_max3_f32 v53, v53, v10, v9
	s_nop 0
	v_cndmask_b32_e32 v8, v172, v7, vcc
	v_add_f32_e32 v7, v65, v249
	v_cmp_gt_u32_e32 vcc, s65, v214
	s_nop 1
	v_cndmask_b32_e32 v7, v172, v7, vcc
	v_max3_f32 v53, v53, v8, v7
	v_mov_b32_e32 v54, v53
	s_nop 1
	v_permlane32_swap_b32_e32 v53, v54
	v_max_f32_e32 v54, v54, v54
	v_max_f32_e32 v53, v53, v53
	v_max_f32_e32 v53, v53, v54
	v_add_f32_e32 v54, 0x41000000, v159
	v_cmp_gt_f32_e32 vcc, v53, v54
	s_cbranch_vccz .LBB0_1289
	v_max_f32_e32 v53, v53, v53
	v_max_f32_e32 v54, v159, v159
	v_max_f32_e32 v53, v54, v53
	v_sub_f32_e32 v54, v159, v53
	v_exp_f32_e32 v54, v54
	v_mov_b32_e32 v159, v53
	v_pk_mul_f32 v[48:49], v[48:49], v[54:55] op_sel_hi:[1,0]
	v_pk_mul_f32 v[46:47], v[46:47], v[54:55] op_sel_hi:[1,0]
	v_pk_mul_f32 v[44:45], v[44:45], v[54:55] op_sel_hi:[1,0]
	v_pk_mul_f32 v[42:43], v[42:43], v[54:55] op_sel_hi:[1,0]
	v_pk_mul_f32 v[40:41], v[40:41], v[54:55] op_sel_hi:[1,0]
	v_pk_mul_f32 v[38:39], v[38:39], v[54:55] op_sel_hi:[1,0]
	v_pk_mul_f32 v[36:37], v[36:37], v[54:55] op_sel_hi:[1,0]
	v_pk_mul_f32 v[34:35], v[34:35], v[54:55] op_sel_hi:[1,0]
	v_pk_mul_f32 v[32:33], v[32:33], v[54:55] op_sel_hi:[1,0]
	v_pk_mul_f32 v[30:31], v[30:31], v[54:55] op_sel_hi:[1,0]
	v_pk_mul_f32 v[28:29], v[28:29], v[54:55] op_sel_hi:[1,0]
	v_pk_mul_f32 v[26:27], v[26:27], v[54:55] op_sel_hi:[1,0]
	v_pk_mul_f32 v[24:25], v[24:25], v[54:55] op_sel_hi:[1,0]
	v_pk_mul_f32 v[22:23], v[22:23], v[54:55] op_sel_hi:[1,0]
	v_pk_mul_f32 v[20:21], v[20:21], v[54:55] op_sel_hi:[1,0]
	v_pk_mul_f32 v[18:19], v[18:19], v[54:55] op_sel_hi:[1,0]
	v_mul_f32_e32 v3, v3, v54
	s_branch .LBB0_1289
